# GEMM phase prologue: the second batch of first-tile LDS-DMAs is issued before the first wait (one cold latency instead of two); on top of v61
# baseline (speedup 1.0000x reference)
; __device__ __forceinline__ int tid_fresh() { int t = threadIdx.x; asm volatile("" : "+v"(t)); return t; }
; #define PG8_WAIT_V(n) asm volatile("s_waitcnt vmcnt(" #n ")" ::: "memory")
; #define PG8_BAR __builtin_amdgcn_s_barrier()
; template <class Epi, class Sched, bool ABLK = false, bool ALIGN_EPI = true, bool SP2 = true, bool BBLK = true>
; __device__ __forceinline__ void gemm_phase(LAS unsigned char* lds, const Gemm g, const Sched& S, const Epi& E) {
;     const int tid = tid_fresh(), wid = __builtin_amdgcn_readfirstlane(tid >> 6), lane = tid & 63, wr = wid >> 2, wc = wid & 3, fr = lane & 15, fq = lane >> 4;
;     unsigned voffA[2], voffB[2];
; #pragma unroll
;     for (int i = 0; i < 2; ++i) { int R, C; stage_rc(tid * 16 + i * 8192, R, C); const int r32 = Epi::PERM ? perm32(R & 31) : (R & 31);
;         const int Rb = Epi::ADJ ? 64 * (R >> 5) + r32 : (R & ~31) + r32;
;         voffA[i] = (unsigned)(R * (ABLK ? 64 : g.lda) + C) * 2u; voffB[i] = BBLK ? (unsigned)(R * 64 + C) * 2u : (unsigned)(Rb * g.ldb + C) * 2u; }
;     const size_t kstep = (size_t)(BK * 2);
;     const size_t hstepA = (size_t)HALF * (ABLK ? 64 : g.lda) * 2, hstepB = BBLK ? (size_t)16384 : (size_t)(Epi::ADJ ? 32 : HALF) * g.ldb * 2;
;     const size_t tstepB = BBLK ? ((size_t)g.ldb / 64) * 32768 : (size_t)BM * g.ldb * 2;
;     const size_t kstepB = BBLK ? (size_t)32768 : kstep;
;     auto b_k0 = [&](int k0) -> size_t { return BBLK ? (size_t)(k0 / BK) * 32768 : (size_t)k0 * 2; };
;     const unsigned ldsw = (unsigned)wid * 1024u;
;     const int aoff = lds_byte(wr * 64 + fr, fq * 8), boff = lds_byte(wc * 32 + fr, fq * 8);
;     ...
;     const char* uA = a_unit(cur); int tbA = cur.k0 / BK;
;     const char* cA = a_tile(uA, tbA); const char* cB = (const char*)g.Bt + (size_t)cur.pn * tstepB + b_k0(cur.k0);
;     S.a_ready(cur);
;     if constexpr (SP2) {
;         PG8_STAGE(PG8_SB(0, 0), cB, voffB); PG8_STAGE(PG8_SB(0, 1), cB + hstepB, voffB); PG8_STAGE(PG8_SA(0, 0), cA, voffA); PG8_STAGE(PG8_SA(0, 1), cA + hstepA, voffA);
;         if (wr == 1) PG8_BAR;
;         PG8_WAIT_V(2); PG8_BAR;
;         PG8_STAGE(PG8_SB(1, 0), cB + kstepB, voffB); PG8_STAGE(PG8_SA(1, 0), a_tile(uA, tbA + 1), voffA); PG8_STAGE(PG8_SB(1, 1), cB + hstepB + kstepB, voffB);
;         PG8_WAIT_V(6); PG8_BAR;
.LBB0_344:
	s_lshl_b32 s6, s6, 5
	s_and_b32 s9, s6, 0x60
	s_lshl_b32 s8, s5, 13
	s_lshl_b32 s10, s9, 7
	s_add_u32 s6, s26, 0x8000
	s_addc_u32 s7, s27, 0
	s_add_i32 m0, s21, 0x18000
	v_lshl_add_u64 v[14:15], s[6:7], 0, v[134:135]
	global_load_lds_dwordx4 v[14:15], off
	v_lshl_add_u64 v[14:15], s[6:7], 0, v[130:131]
	s_add_i32 m0, s21, 0x1a000
	s_mov_b64 s[6:7], 0x80
	s_add_i32 s42, s21, 0x8000
	global_load_lds_dwordx4 v[14:15], off
	v_lshl_add_u64 v[2:3], v[2:3], 0, s[6:7]
	s_mov_b32 m0, s42
	s_add_i32 s43, s21, 0xa000
	global_load_lds_dwordx4 v[2:3], off
	v_lshl_add_u64 v[2:3], v[4:5], 0, s[6:7]
	s_add_u32 s6, s26, 0xc000
	s_mov_b32 m0, s43
	s_addc_u32 s7, s27, 0
	global_load_lds_dwordx4 v[2:3], off
	s_add_i32 m0, s21, 0x1c000
	s_nop 0
	global_load_lds_dwordx4 v134, s[6:7]
	s_add_i32 m0, s21, 0x1e000
	s_cmpk_lt_u32 s4, 0x100
	global_load_lds_dwordx4 v130, s[6:7]
	s_waitcnt vmcnt(8)
	s_barrier
	v_lshrrev_b32_e32 v3, 1, v6
	v_and_b32_e32 v3, 24, v3
	v_and_b32_e32 v2, 15, v6
	v_lshlrev_b32_e32 v4, 1, v3
	v_lshl_or_b32 v1, s5, 6, v2
	v_lshl_or_b32 v2, v2, 6, v4
	v_lshlrev_b32_e32 v4, 2, v6
	v_and_b32_e32 v4, 32, v4
	v_bitop3_b32 v5, v2, s8, v4 bitop3:0xde
	v_bitop3_b32 v146, v2, s10, v4 bitop3:0xde
	v_lshlrev_b32_e32 v2, 15, v10
	v_and_b32_e32 v2, 0xffff0000, v2
	v_or_b32_e32 v147, s9, v3
	v_lshl_add_u32 v2, v11, 12, v2
	v_and_b32_e32 v3, 1, v10
	v_lshl_or_b32 v2, v3, 6, v2
	v_lshl_add_u32 v2, v12, 1, v2
	v_mov_b32_e32 v3, v135
	s_mov_b64 s[4:5], 0x80080
	v_lshl_add_u64 v[138:139], v[2:3], 0, s[4:5]
	v_lshlrev_b32_e32 v2, 15, v7
	v_and_b32_e32 v2, 0xffff0000, v2
	v_lshl_add_u32 v2, v8, 12, v2
	v_and_b32_e32 v3, 1, v7
	s_waitcnt vmcnt(6)
	v_lshl_or_b32 v2, v3, 6, v2
	s_cselect_b64 s[6:7], -1, 0
	v_lshl_add_u32 v2, v9, 1, v2
	v_mov_b32_e32 v3, v135
	s_add_i32 s44, 0, 0x10000
	s_add_i32 s45, 0, 0x14000
	v_lshl_add_u64 v[140:141], v[2:3], 0, s[4:5]
	v_add_u32_e32 v148, s44, v146
	v_add_u32_e32 v149, s45, v146
	v_add_u32_e32 v150, 0, v5
	s_mov_b32 s46, 0x80000
	s_mov_b32 s47, 0x90000
	s_mov_b32 s48, 0xa0000
	s_add_i32 s49, s21, 0xc000
	s_barrier
	s_branch .LBB0_347

; __device__ __forceinline__ int tid_fresh() { int t = threadIdx.x; asm volatile("" : "+v"(t)); return t; }
; #define PG8_WAIT_V(n) asm volatile("s_waitcnt vmcnt(" #n ")" ::: "memory")
; #define PG8_BAR __builtin_amdgcn_s_barrier()
; template <class Epi, class Sched, bool ABLK = false, bool ALIGN_EPI = true, bool SP2 = true, bool BBLK = true>
; __device__ __forceinline__ void gemm_phase(LAS unsigned char* lds, const Gemm g, const Sched& S, const Epi& E) {
;     const int tid = tid_fresh(), wid = __builtin_amdgcn_readfirstlane(tid >> 6), lane = tid & 63, wr = wid >> 2, wc = wid & 3, fr = lane & 15, fq = lane >> 4;
;     unsigned voffA[2], voffB[2];
; #pragma unroll
;     for (int i = 0; i < 2; ++i) { int R, C; stage_rc(tid * 16 + i * 8192, R, C); const int r32 = Epi::PERM ? perm32(R & 31) : (R & 31);
;         const int Rb = Epi::ADJ ? 64 * (R >> 5) + r32 : (R & ~31) + r32;
;         voffA[i] = (unsigned)(R * (ABLK ? 64 : g.lda) + C) * 2u; voffB[i] = BBLK ? (unsigned)(R * 64 + C) * 2u : (unsigned)(Rb * g.ldb + C) * 2u; }
;     const size_t kstep = (size_t)(BK * 2);
;     const size_t hstepA = (size_t)HALF * (ABLK ? 64 : g.lda) * 2, hstepB = BBLK ? (size_t)16384 : (size_t)(Epi::ADJ ? 32 : HALF) * g.ldb * 2;
;     const size_t tstepB = BBLK ? ((size_t)g.ldb / 64) * 32768 : (size_t)BM * g.ldb * 2;
;     const size_t kstepB = BBLK ? (size_t)32768 : kstep;
;     auto b_k0 = [&](int k0) -> size_t { return BBLK ? (size_t)(k0 / BK) * 32768 : (size_t)k0 * 2; };
;     const unsigned ldsw = (unsigned)wid * 1024u;
;     const int aoff = lds_byte(wr * 64 + fr, fq * 8), boff = lds_byte(wc * 32 + fr, fq * 8);
;     ...
;     const char* uA = a_unit(cur); int tbA = cur.k0 / BK;
;     const char* cA = a_tile(uA, tbA); const char* cB = (const char*)g.Bt + (size_t)cur.pn * tstepB + b_k0(cur.k0);
;     S.a_ready(cur);
;     if constexpr (SP2) {
;         PG8_STAGE(PG8_SB(0, 0), cB, voffB); PG8_STAGE(PG8_SB(0, 1), cB + hstepB, voffB); PG8_STAGE(PG8_SA(0, 0), cA, voffA); PG8_STAGE(PG8_SA(0, 1), cA + hstepA, voffA);
;         if (wr == 1) PG8_BAR;
;         PG8_WAIT_V(2); PG8_BAR;
;         PG8_STAGE(PG8_SB(1, 0), cB + kstepB, voffB); PG8_STAGE(PG8_SA(1, 0), a_tile(uA, tbA + 1), voffA); PG8_STAGE(PG8_SB(1, 1), cB + hstepB + kstepB, voffB);
;         PG8_WAIT_V(6); PG8_BAR;
.LBB0_469:
	s_and_b32 s49, s8, 3
	s_lshl_b32 s10, s7, 13
	s_lshl_b32 s11, s49, 12
	s_add_u32 s8, s28, 0x8000
	s_addc_u32 s9, s29, 0
	s_add_i32 m0, s25, 0x18000
	v_lshl_add_u64 v[12:13], s[8:9], 0, v[134:135]
	global_load_lds_dwordx4 v[12:13], off
	v_lshl_add_u64 v[12:13], s[8:9], 0, v[130:131]
	s_add_i32 m0, s25, 0x1a000
	s_mov_b64 s[8:9], 0x80
	s_add_i32 s50, s25, 0x8000
	global_load_lds_dwordx4 v[12:13], off
	v_lshl_add_u64 v[2:3], v[2:3], 0, s[8:9]
	s_mov_b32 m0, s50
	s_add_i32 s51, s25, 0xa000
	global_load_lds_dwordx4 v[2:3], off
	v_lshl_add_u64 v[2:3], v[4:5], 0, s[8:9]
	s_add_u32 s8, s28, 0xc000
	s_mov_b32 m0, s51
	s_addc_u32 s9, s29, 0
	global_load_lds_dwordx4 v[2:3], off
	s_add_i32 m0, s25, 0x1c000
	s_nop 0
	global_load_lds_dwordx4 v134, s[8:9]
	s_add_i32 m0, s25, 0x1e000
	v_lshrrev_b32_e32 v4, 1, v1
	global_load_lds_dwordx4 v130, s[8:9]
	s_waitcnt vmcnt(8)
	s_barrier
	v_and_b32_e32 v4, 24, v4
	v_and_b32_e32 v3, 15, v1
	v_lshlrev_b32_e32 v5, 1, v4
	v_lshl_or_b32 v2, s7, 6, v3
	v_lshl_or_b32 v5, v3, 6, v5
	s_cmpk_lt_u32 s6, 0x100
	v_cmp_lt_u32_e64 s[6:7], 7, v3
	v_mov_b32_e32 v3, 0xfffffc40
	v_or_b32_e32 v12, 16, v2
	v_cndmask_b32_e64 v140, 0, v3, s[6:7]
	v_mov_b32_e32 v3, 0x400
	v_cndmask_b32_e64 v142, v3, 64, s[6:7]
	v_ashrrev_i32_e32 v3, 31, v2
	v_ashrrev_i32_e32 v13, 31, v12
	v_lshlrev_b64 v[144:145], 7, v[2:3]
	v_lshlrev_b64 v[146:147], 7, v[12:13]
	v_or_b32_e32 v12, 32, v2
	v_or_b32_e32 v2, 48, v2
	v_ashrrev_i32_e32 v3, 31, v2
	v_lshlrev_b64 v[150:151], 7, v[2:3]
	v_lshlrev_b32_e32 v2, 15, v9
	v_and_b32_e32 v2, 0xffff0000, v2
	v_lshl_add_u32 v2, v10, 12, v2
	v_and_b32_e32 v3, 1, v9
	v_lshl_or_b32 v2, v3, 6, v2
	v_lshl_add_u64 v[152:153], v[144:145], 0, s[4:5]
	s_mov_b64 s[4:5], 0x4800
	v_lshl_add_u32 v138, v11, 1, v2
	v_lshlrev_b32_e32 v2, 15, v6
	v_lshlrev_b32_e32 v1, 2, v1
	v_lshl_add_u64 v[154:155], v[144:145], 0, s[4:5]
	s_mov_b64 s[4:5], 0x5000
	v_and_b32_e32 v2, 0xffff0000, v2
	v_and_b32_e32 v1, 32, v1
	v_lshl_add_u64 v[156:157], v[144:145], 0, s[4:5]
	s_mov_b64 s[4:5], 0x5800
	v_lshl_add_u32 v2, v7, 12, v2
	v_and_b32_e32 v3, 1, v6
	v_bitop3_b32 v14, v5, s10, v1 bitop3:0xde
	v_bitop3_b32 v1, v5, s11, v1 bitop3:0xde
	s_waitcnt vmcnt(6)
	s_cselect_b64 s[8:9], -1, 0
	v_lshl_add_u64 v[158:159], v[144:145], 0, s[4:5]
	s_mov_b64 s[4:5], 0x80080
	v_lshl_or_b32 v2, v3, 6, v2
	s_add_i32 s55, 0, 0x10000
	v_ashrrev_i32_e32 v13, 31, v12
	v_lshl_add_u64 v[160:161], v[138:139], 0, s[4:5]
	v_lshl_add_u32 v138, v8, 1, v2
	s_add_i32 s52, 0, 0x14000
	v_add_u32_e32 v168, s55, v1
	s_add_i32 s55, s55, s40
	v_cndmask_b32_e64 v141, 0, -1, s[6:7]
	v_mov_b32_e32 v143, v139
	v_lshlrev_b64 v[148:149], 7, v[12:13]
	v_lshl_add_u64 v[162:163], v[138:139], 0, s[4:5]
	v_add_u32_e32 v169, s52, v1
	v_add_u32_e32 v170, 0, v14
	v_lshlrev_b32_e32 v138, 1, v4
	s_add_i32 s53, s25, 0xc000
	s_add_i32 s54, s25, 0xe000
	s_add_i32 s56, s55, 0x2000
	s_barrier
	s_branch .LBB0_472

; __device__ __forceinline__ int tid_fresh() { int t = threadIdx.x; asm volatile("" : "+v"(t)); return t; }
; #define PG8_WAIT_V(n) asm volatile("s_waitcnt vmcnt(" #n ")" ::: "memory")
; #define PG8_BAR __builtin_amdgcn_s_barrier()
; template <class Epi, class Sched, bool ABLK = false, bool ALIGN_EPI = true, bool SP2 = true, bool BBLK = true>
; __device__ __forceinline__ void gemm_phase(LAS unsigned char* lds, const Gemm g, const Sched& S, const Epi& E) {
;     const int tid = tid_fresh(), wid = __builtin_amdgcn_readfirstlane(tid >> 6), lane = tid & 63, wr = wid >> 2, wc = wid & 3, fr = lane & 15, fq = lane >> 4;
;     unsigned voffA[2], voffB[2];
; #pragma unroll
;     for (int i = 0; i < 2; ++i) { int R, C; stage_rc(tid * 16 + i * 8192, R, C); const int r32 = Epi::PERM ? perm32(R & 31) : (R & 31);
;         const int Rb = Epi::ADJ ? 64 * (R >> 5) + r32 : (R & ~31) + r32;
;         voffA[i] = (unsigned)(R * (ABLK ? 64 : g.lda) + C) * 2u; voffB[i] = BBLK ? (unsigned)(R * 64 + C) * 2u : (unsigned)(Rb * g.ldb + C) * 2u; }
;     const size_t kstep = (size_t)(BK * 2);
;     const size_t hstepA = (size_t)HALF * (ABLK ? 64 : g.lda) * 2, hstepB = BBLK ? (size_t)16384 : (size_t)(Epi::ADJ ? 32 : HALF) * g.ldb * 2;
;     const size_t tstepB = BBLK ? ((size_t)g.ldb / 64) * 32768 : (size_t)BM * g.ldb * 2;
;     const size_t kstepB = BBLK ? (size_t)32768 : kstep;
;     auto b_k0 = [&](int k0) -> size_t { return BBLK ? (size_t)(k0 / BK) * 32768 : (size_t)k0 * 2; };
;     const unsigned ldsw = (unsigned)wid * 1024u;
;     const int aoff = lds_byte(wr * 64 + fr, fq * 8), boff = lds_byte(wc * 32 + fr, fq * 8);
;     ...
;     const char* uA = a_unit(cur); int tbA = cur.k0 / BK;
;     const char* cA = a_tile(uA, tbA); const char* cB = (const char*)g.Bt + (size_t)cur.pn * tstepB + b_k0(cur.k0);
;     S.a_ready(cur);
;     if constexpr (SP2) {
;         PG8_STAGE(PG8_SB(0, 0), cB, voffB); PG8_STAGE(PG8_SB(0, 1), cB + hstepB, voffB); PG8_STAGE(PG8_SA(0, 0), cA, voffA); PG8_STAGE(PG8_SA(0, 1), cA + hstepA, voffA);
;         if (wr == 1) PG8_BAR;
;         PG8_WAIT_V(2); PG8_BAR;
;         PG8_STAGE(PG8_SB(1, 0), cB + kstepB, voffB); PG8_STAGE(PG8_SA(1, 0), a_tile(uA, tbA + 1), voffA); PG8_STAGE(PG8_SB(1, 1), cB + hstepB + kstepB, voffB);
;         PG8_WAIT_V(6); PG8_BAR;
.LBB0_536:
	s_and_b32 s8, s5, 3
	s_lshl_b32 s5, s4, 13
	s_lshl_b32 s9, s8, 12
	s_add_u32 s10, s68, 0x3c900000
	s_addc_u32 s11, s69, 0
	s_add_u32 s6, s40, 0x8000
	s_addc_u32 s7, s41, 0
	s_add_i32 m0, s52, 0x18000
	v_lshl_add_u64 v[10:11], s[6:7], 0, v[130:131]
	global_load_lds_dwordx4 v[10:11], off
	s_add_i32 m0, s52, 0x1a000
	v_lshl_add_u64 v[10:11], s[6:7], 0, v[132:133]
	s_add_u32 s6, s42, 0x8000
	s_addc_u32 s7, s43, 0
	s_add_i32 s56, s52, 0x8000
	global_load_lds_dwordx4 v[10:11], off
	s_mov_b32 m0, s56
	s_add_i32 s57, s52, 0xa000
	global_load_lds_dwordx4 v130, s[6:7]
	v_lshl_add_u64 v[10:11], s[6:7], 0, v[132:133]
	s_add_u32 s6, s40, 0xc000
	s_mov_b32 m0, s57
	s_addc_u32 s7, s41, 0
	global_load_lds_dwordx4 v[10:11], off
	s_add_i32 m0, s52, 0x1c000
	s_nop 0
	global_load_lds_dwordx4 v130, s[6:7]
	s_add_i32 m0, s52, 0x1e000
	v_and_b32_e32 v9, 15, v6
	global_load_lds_dwordx4 v132, s[6:7]
	s_waitcnt vmcnt(8)
	s_barrier
	v_lshrrev_b32_e32 v10, 1, v6
	v_and_b32_e32 v10, 24, v10
	v_lshlrev_b32_e32 v11, 1, v10
	v_lshl_or_b32 v1, s4, 6, v9
	v_lshl_or_b32 v11, v9, 6, v11
	v_cmp_lt_u32_e64 s[6:7], 7, v9
	v_mov_b32_e32 v9, 0xffff8040
	v_lshlrev_b32_e32 v6, 2, v6
	v_cndmask_b32_e64 v134, 0, v9, s[6:7]
	v_mov_b32_e32 v9, 0x8000
	v_cndmask_b32_e64 v136, v9, 64, s[6:7]
	v_lshlrev_b32_e32 v9, 10, v2
	v_and_b32_e32 v9, 0xfffff800, v9
	v_lshl_add_u32 v3, v3, 7, v9
	v_and_b32_e32 v2, 1, v2
	v_and_b32_e32 v6, 32, v6
	v_lshl_or_b32 v2, v2, 6, v3
	v_bitop3_b32 v146, v11, s9, v6 bitop3:0xde
	v_bitop3_b32 v6, v11, s5, v6 bitop3:0xde
	s_mov_b64 s[4:5], 0xc000
	v_lshl_add_u32 v2, v4, 1, v2
	v_mov_b32_e32 v3, v131
	v_lshl_add_u64 v[138:139], v[2:3], 0, s[4:5]
	v_lshlrev_b32_e32 v2, 10, v5
	v_and_b32_e32 v2, 0xfffff800, v2
	v_lshl_add_u32 v2, v7, 7, v2
	v_and_b32_e32 v3, 1, v5
	s_waitcnt vmcnt(6)
	s_cmpk_lt_u32 s0, 0x100
	v_lshl_or_b32 v2, v3, 6, v2
	s_cselect_b64 s[12:13], -1, 0
	s_bfe_u32 s71, s90, 0x20006
	s_ashr_i32 s0, s82, 2
	v_lshl_add_u32 v2, v8, 1, v2
	v_mov_b32_e32 v3, v131
	s_add_i32 s72, 0, 0x10000
	s_add_i32 s73, 0, 0x14000
	v_cndmask_b32_e64 v135, 0, -1, s[6:7]
	v_mov_b32_e32 v137, v131
	s_add_i32 s80, s0, 32
	s_lshl_b32 s0, s71, 11
	v_lshl_or_b32 v147, s8, 6, v10
	v_lshl_add_u64 v[140:141], v[2:3], 0, s[4:5]
	s_mov_b64 s[4:5], -1
	s_movk_i32 s59, 0x80
	s_mov_b64 s[14:15], 0x10000
	v_add_u32_e32 v148, s72, v146
	v_add_u32_e32 v149, s73, v146
	v_add_u32_e32 v150, 0, v6
	s_mov_b64 s[18:19], 0x20000
	s_mov_b64 s[20:21], 0x30000
	s_mov_b64 s[22:23], 0x80000
	s_mov_b64 s[24:25], 0x90000
	s_mov_b64 s[26:27], 0xa0000
	s_mov_b64 s[28:29], 0xb0000
	s_mov_b32 s62, s82
	s_mov_b32 s46, 0
	s_barrier
	s_branch .LBB0_539

; __device__ __forceinline__ int tid_fresh() { int t = threadIdx.x; asm volatile("" : "+v"(t)); return t; }
; #define PG8_WAIT_V(n) asm volatile("s_waitcnt vmcnt(" #n ")" ::: "memory")
; #define PG8_BAR __builtin_amdgcn_s_barrier()
; template <class Epi, class Sched, bool ABLK = false, bool ALIGN_EPI = true, bool SP2 = true, bool BBLK = true>
; __device__ __forceinline__ void gemm_phase(LAS unsigned char* lds, const Gemm g, const Sched& S, const Epi& E) {
;     const int tid = tid_fresh(), wid = __builtin_amdgcn_readfirstlane(tid >> 6), lane = tid & 63, wr = wid >> 2, wc = wid & 3, fr = lane & 15, fq = lane >> 4;
;     unsigned voffA[2], voffB[2];
; #pragma unroll
;     for (int i = 0; i < 2; ++i) { int R, C; stage_rc(tid * 16 + i * 8192, R, C); const int r32 = Epi::PERM ? perm32(R & 31) : (R & 31);
;         const int Rb = Epi::ADJ ? 64 * (R >> 5) + r32 : (R & ~31) + r32;
;         voffA[i] = (unsigned)(R * (ABLK ? 64 : g.lda) + C) * 2u; voffB[i] = BBLK ? (unsigned)(R * 64 + C) * 2u : (unsigned)(Rb * g.ldb + C) * 2u; }
;     const size_t kstep = (size_t)(BK * 2);
;     const size_t hstepA = (size_t)HALF * (ABLK ? 64 : g.lda) * 2, hstepB = BBLK ? (size_t)16384 : (size_t)(Epi::ADJ ? 32 : HALF) * g.ldb * 2;
;     const size_t tstepB = BBLK ? ((size_t)g.ldb / 64) * 32768 : (size_t)BM * g.ldb * 2;
;     const size_t kstepB = BBLK ? (size_t)32768 : kstep;
;     auto b_k0 = [&](int k0) -> size_t { return BBLK ? (size_t)(k0 / BK) * 32768 : (size_t)k0 * 2; };
;     const unsigned ldsw = (unsigned)wid * 1024u;
;     const int aoff = lds_byte(wr * 64 + fr, fq * 8), boff = lds_byte(wc * 32 + fr, fq * 8);
;     ...
;     const char* uA = a_unit(cur); int tbA = cur.k0 / BK;
;     const char* cA = a_tile(uA, tbA); const char* cB = (const char*)g.Bt + (size_t)cur.pn * tstepB + b_k0(cur.k0);
;     S.a_ready(cur);
;     if constexpr (SP2) {
;         PG8_STAGE(PG8_SB(0, 0), cB, voffB); PG8_STAGE(PG8_SB(0, 1), cB + hstepB, voffB); PG8_STAGE(PG8_SA(0, 0), cA, voffA); PG8_STAGE(PG8_SA(0, 1), cA + hstepA, voffA);
;         if (wr == 1) PG8_BAR;
;         PG8_WAIT_V(2); PG8_BAR;
;         PG8_STAGE(PG8_SB(1, 0), cB + kstepB, voffB); PG8_STAGE(PG8_SA(1, 0), a_tile(uA, tbA + 1), voffA); PG8_STAGE(PG8_SB(1, 1), cB + hstepB + kstepB, voffB);
;         PG8_WAIT_V(6); PG8_BAR;
.LBB0_662:
	s_and_b32 s2, s2, 3
	s_lshl_b32 s9, s5, 13
	s_lshl_b32 s12, s2, 12
	s_add_u32 s6, s28, 0x8000
	s_addc_u32 s7, s29, 0
	s_add_i32 m0, s25, 0x18000
	v_lshl_add_u64 v[12:13], s[6:7], 0, v[132:133]
	global_load_lds_dwordx4 v[12:13], off
	v_lshl_add_u64 v[12:13], s[6:7], 0, v[136:137]
	s_add_i32 m0, s25, 0x1a000
	s_mov_b64 s[6:7], 0x80
	s_add_i32 s47, s25, 0x8000
	global_load_lds_dwordx4 v[12:13], off
	v_lshl_add_u64 v[2:3], v[2:3], 0, s[6:7]
	s_mov_b32 m0, s47
	s_add_i32 s48, s25, 0xa000
	global_load_lds_dwordx4 v[2:3], off
	v_lshl_add_u64 v[2:3], v[4:5], 0, s[6:7]
	s_add_u32 s6, s28, 0xc000
	s_mov_b32 m0, s48
	s_addc_u32 s7, s29, 0
	global_load_lds_dwordx4 v[2:3], off
	s_add_i32 m0, s25, 0x1c000
	s_nop 0
	global_load_lds_dwordx4 v132, s[6:7]
	s_add_i32 m0, s25, 0x1e000
	s_cmpk_lt_u32 s4, 0x100
	global_load_lds_dwordx4 v136, s[6:7]
	s_waitcnt vmcnt(8)
	s_barrier
	v_lshrrev_b32_e32 v3, 1, v1
	v_and_b32_e32 v3, 24, v3
	v_and_b32_e32 v2, 15, v1
	v_lshlrev_b32_e32 v4, 1, v3
	v_lshl_or_b32 v140, s5, 6, v2
	v_lshl_or_b32 v4, v2, 6, v4
	v_cmp_lt_u32_e64 s[6:7], 7, v2
	v_mov_b32_e32 v2, 0xffff8040
	v_ashrrev_i32_e32 v141, 31, v140
	v_cndmask_b32_e64 v142, 0, v2, s[6:7]
	v_mov_b32_e32 v2, 0x8000
	v_cndmask_b32_e64 v144, v2, 64, s[6:7]
	v_lshlrev_b32_e32 v2, 15, v6
	v_and_b32_e32 v2, 0xffff0000, v2
	v_lshlrev_b64 v[146:147], 13, v[140:141]
	v_lshl_or_b32 v141, s2, 6, v3
	v_lshl_add_u32 v2, v7, 12, v2
	v_and_b32_e32 v3, 1, v6
	v_lshl_or_b32 v2, v3, 6, v2
	v_lshl_add_u32 v138, v8, 1, v2
	v_lshlrev_b32_e32 v2, 15, v9
	v_and_b32_e32 v2, 0xffff0000, v2
	v_lshlrev_b32_e32 v1, 2, v1
	v_lshl_add_u32 v2, v10, 12, v2
	v_and_b32_e32 v3, 1, v9
	v_and_b32_e32 v1, 32, v1
	s_waitcnt vmcnt(6)
	v_or_b32_e32 v148, 16, v140
	v_or_b32_e32 v152, 32, v140
	v_or_b32_e32 v156, 48, v140
	v_add_u32_e32 v160, 0x80, v140
	v_add_u32_e32 v164, 0x90, v140
	v_add_u32_e32 v168, 0xa0, v140
	v_add_u32_e32 v172, 0xb0, v140
	s_mov_b64 s[4:5], 0x80080
	v_lshl_or_b32 v2, v3, 6, v2
	v_bitop3_b32 v5, v4, s9, v1 bitop3:0xde
	v_bitop3_b32 v1, v4, s12, v1 bitop3:0xde
	v_ashrrev_i32_e32 v149, 31, v148
	v_ashrrev_i32_e32 v153, 31, v152
	v_ashrrev_i32_e32 v157, 31, v156
	v_ashrrev_i32_e32 v161, 31, v160
	v_ashrrev_i32_e32 v165, 31, v164
	v_ashrrev_i32_e32 v169, 31, v168
	v_ashrrev_i32_e32 v173, 31, v172
	v_lshl_add_u64 v[176:177], v[138:139], 0, s[4:5]
	v_lshl_add_u32 v138, v11, 1, v2
	s_cselect_b64 s[12:13], -1, 0
	v_cndmask_b32_e64 v143, 0, -1, s[6:7]
	v_mov_b32_e32 v145, v139
	v_lshlrev_b64 v[150:151], 13, v[148:149]
	v_lshlrev_b64 v[154:155], 13, v[152:153]
	v_lshlrev_b64 v[158:159], 13, v[156:157]
	v_lshlrev_b64 v[162:163], 13, v[160:161]
	v_lshlrev_b64 v[166:167], 13, v[164:165]
	v_lshlrev_b64 v[170:171], 13, v[168:169]
	v_lshlrev_b64 v[174:175], 13, v[172:173]
	v_lshl_add_u64 v[178:179], v[138:139], 0, s[4:5]
	v_add_u32_e32 v149, 0, v5
	s_mov_b32 s49, 0x7880000
	s_mov_b32 s50, 0x5080000
	v_add_u32_e32 v153, s72, v1
	v_add_u32_e32 v157, s73, v1
	s_mov_b32 s51, 0
	s_barrier
	s_branch .LBB0_665

; __device__ __forceinline__ int tid_fresh() { int t = threadIdx.x; asm volatile("" : "+v"(t)); return t; }
; #define PG8_WAIT_V(n) asm volatile("s_waitcnt vmcnt(" #n ")" ::: "memory")
; #define PG8_BAR __builtin_amdgcn_s_barrier()
; template <class Epi, class Sched, bool ABLK = false, bool ALIGN_EPI = true, bool SP2 = true, bool BBLK = true>
; __device__ __forceinline__ void gemm_phase(LAS unsigned char* lds, const Gemm g, const Sched& S, const Epi& E) {
;     const int tid = tid_fresh(), wid = __builtin_amdgcn_readfirstlane(tid >> 6), lane = tid & 63, wr = wid >> 2, wc = wid & 3, fr = lane & 15, fq = lane >> 4;
;     unsigned voffA[2], voffB[2];
; #pragma unroll
;     for (int i = 0; i < 2; ++i) { int R, C; stage_rc(tid * 16 + i * 8192, R, C); const int r32 = Epi::PERM ? perm32(R & 31) : (R & 31);
;         const int Rb = Epi::ADJ ? 64 * (R >> 5) + r32 : (R & ~31) + r32;
;         voffA[i] = (unsigned)(R * (ABLK ? 64 : g.lda) + C) * 2u; voffB[i] = BBLK ? (unsigned)(R * 64 + C) * 2u : (unsigned)(Rb * g.ldb + C) * 2u; }
;     const size_t kstep = (size_t)(BK * 2);
;     const size_t hstepA = (size_t)HALF * (ABLK ? 64 : g.lda) * 2, hstepB = BBLK ? (size_t)16384 : (size_t)(Epi::ADJ ? 32 : HALF) * g.ldb * 2;
;     const size_t tstepB = BBLK ? ((size_t)g.ldb / 64) * 32768 : (size_t)BM * g.ldb * 2;
;     const size_t kstepB = BBLK ? (size_t)32768 : kstep;
;     auto b_k0 = [&](int k0) -> size_t { return BBLK ? (size_t)(k0 / BK) * 32768 : (size_t)k0 * 2; };
;     const unsigned ldsw = (unsigned)wid * 1024u;
;     const int aoff = lds_byte(wr * 64 + fr, fq * 8), boff = lds_byte(wc * 32 + fr, fq * 8);
;     ...
;     const char* uA = a_unit(cur); int tbA = cur.k0 / BK;
;     const char* cA = a_tile(uA, tbA); const char* cB = (const char*)g.Bt + (size_t)cur.pn * tstepB + b_k0(cur.k0);
;     S.a_ready(cur);
;     if constexpr (SP2) {
;         PG8_STAGE(PG8_SB(0, 0), cB, voffB); PG8_STAGE(PG8_SB(0, 1), cB + hstepB, voffB); PG8_STAGE(PG8_SA(0, 0), cA, voffA); PG8_STAGE(PG8_SA(0, 1), cA + hstepA, voffA);
;         if (wr == 1) PG8_BAR;
;         PG8_WAIT_V(2); PG8_BAR;
;         PG8_STAGE(PG8_SB(1, 0), cB + kstepB, voffB); PG8_STAGE(PG8_SA(1, 0), a_tile(uA, tbA + 1), voffA); PG8_STAGE(PG8_SB(1, 1), cB + hstepB + kstepB, voffB);
;         PG8_WAIT_V(6); PG8_BAR;
.LBB0_1034:
	s_and_b32 s5, s5, 3
	v_readlane_b32 s12, v252, 19
	s_lshl_b32 s7, s6, 13
	s_lshl_b32 s10, s5, 12
	v_readlane_b32 s14, v252, 21
	v_readlane_b32 s15, v252, 22
	s_add_u32 s52, s14, 0x1e100000
	s_addc_u32 s54, s15, 0
	v_readlane_b32 s13, v252, 20
	s_add_u32 s12, s14, 0x3c900000
	s_addc_u32 s13, s15, 0
	s_add_u32 s8, s20, 0x8000
	s_addc_u32 s9, s21, 0
	s_add_i32 m0, s35, 0x18000
	v_lshl_add_u64 v[14:15], s[8:9], 0, v[132:133]
	global_load_lds_dwordx4 v[14:15], off
	v_lshl_add_u64 v[14:15], s[8:9], 0, v[136:137]
	s_add_i32 m0, s35, 0x1a000
	s_mov_b64 s[8:9], 0x80
	s_add_i32 s41, s35, 0x8000
	global_load_lds_dwordx4 v[14:15], off
	v_lshl_add_u64 v[2:3], v[2:3], 0, s[8:9]
	s_mov_b32 m0, s41
	s_add_i32 s42, s35, 0xa000
	global_load_lds_dwordx4 v[2:3], off
	v_lshl_add_u64 v[2:3], v[4:5], 0, s[8:9]
	s_add_u32 s8, s20, 0xc000
	s_mov_b32 m0, s42
	s_addc_u32 s9, s21, 0
	global_load_lds_dwordx4 v[2:3], off
	s_add_i32 m0, s35, 0x1c000
	s_nop 0
	global_load_lds_dwordx4 v132, s[8:9]
	s_add_i32 m0, s35, 0x1e000
	v_lshlrev_b32_e32 v5, 2, v8
	global_load_lds_dwordx4 v136, s[8:9]
	s_waitcnt vmcnt(8)
	s_barrier
	v_lshrrev_b32_e32 v3, 1, v8
	v_and_b32_e32 v3, 24, v3
	v_and_b32_e32 v2, 15, v8
	v_lshlrev_b32_e32 v4, 1, v3
	v_lshl_or_b32 v4, v2, 6, v4
	v_and_b32_e32 v5, 32, v5
	v_lshl_or_b32 v150, s6, 6, v2
	v_bitop3_b32 v151, v4, s10, v5 bitop3:0xde
	v_bitop3_b32 v4, v4, s7, v5 bitop3:0xde
	v_cmp_lt_u32_e64 s[6:7], 7, v2
	v_mov_b32_e32 v2, 0xffff8040
	v_lshl_or_b32 v152, s5, 6, v3
	v_cndmask_b32_e64 v138, 0, v2, s[6:7]
	v_mov_b32_e32 v2, 0x8000
	v_cndmask_b32_e64 v140, v2, 64, s[6:7]
	v_lshlrev_b32_e32 v2, 15, v6
	v_and_b32_e32 v2, 0xffff0000, v2
	v_lshl_add_u32 v2, v7, 12, v2
	v_and_b32_e32 v3, 1, v6
	v_lshl_or_b32 v2, v3, 6, v2
	s_cmpk_lt_u32 s4, 0x100
	v_lshl_add_u32 v2, v9, 1, v2
	v_mov_b32_e32 v3, v133
	s_mov_b64 s[4:5], 0x80080
	v_lshl_add_u64 v[142:143], v[2:3], 0, s[4:5]
	v_lshlrev_b32_e32 v2, 15, v10
	v_and_b32_e32 v2, 0xffff0000, v2
	v_lshl_add_u32 v2, v11, 12, v2
	v_and_b32_e32 v3, 1, v10
	s_waitcnt vmcnt(6)
	v_lshl_or_b32 v2, v3, 6, v2
	v_lshl_add_u32 v2, v12, 1, v2
	v_mov_b32_e32 v3, v133
	s_cselect_b64 s[10:11], -1, 0
	v_cndmask_b32_e64 v139, 0, -1, s[6:7]
	v_mov_b32_e32 v141, v133
	s_lshl_b32 s63, s71, 9
	v_lshl_add_u64 v[144:145], v[2:3], 0, s[4:5]
	s_mov_b64 s[4:5], -1
	v_add_u32_e32 v153, s72, v151
	v_add_u32_e32 v154, s73, v151
	v_add_u32_e32 v155, 0, v4
	s_mov_b32 s47, s82
	s_mov_b32 s24, 0
	s_barrier
	s_branch .LBB0_1037

; __device__ __forceinline__ int tid_fresh() { int t = threadIdx.x; asm volatile("" : "+v"(t)); return t; }
; #define PG8_WAIT_V(n) asm volatile("s_waitcnt vmcnt(" #n ")" ::: "memory")
; #define PG8_BAR __builtin_amdgcn_s_barrier()
; template <class Epi, class Sched, bool ABLK = false, bool ALIGN_EPI = true, bool SP2 = true, bool BBLK = true>
; __device__ __forceinline__ void gemm_phase(LAS unsigned char* lds, const Gemm g, const Sched& S, const Epi& E) {
;     const int tid = tid_fresh(), wid = __builtin_amdgcn_readfirstlane(tid >> 6), lane = tid & 63, wr = wid >> 2, wc = wid & 3, fr = lane & 15, fq = lane >> 4;
;     unsigned voffA[2], voffB[2];
; #pragma unroll
;     for (int i = 0; i < 2; ++i) { int R, C; stage_rc(tid * 16 + i * 8192, R, C); const int r32 = Epi::PERM ? perm32(R & 31) : (R & 31);
;         const int Rb = Epi::ADJ ? 64 * (R >> 5) + r32 : (R & ~31) + r32;
;         voffA[i] = (unsigned)(R * (ABLK ? 64 : g.lda) + C) * 2u; voffB[i] = BBLK ? (unsigned)(R * 64 + C) * 2u : (unsigned)(Rb * g.ldb + C) * 2u; }
;     const size_t kstep = (size_t)(BK * 2);
;     const size_t hstepA = (size_t)HALF * (ABLK ? 64 : g.lda) * 2, hstepB = BBLK ? (size_t)16384 : (size_t)(Epi::ADJ ? 32 : HALF) * g.ldb * 2;
;     const size_t tstepB = BBLK ? ((size_t)g.ldb / 64) * 32768 : (size_t)BM * g.ldb * 2;
;     const size_t kstepB = BBLK ? (size_t)32768 : kstep;
;     auto b_k0 = [&](int k0) -> size_t { return BBLK ? (size_t)(k0 / BK) * 32768 : (size_t)k0 * 2; };
;     const unsigned ldsw = (unsigned)wid * 1024u;
;     const int aoff = lds_byte(wr * 64 + fr, fq * 8), boff = lds_byte(wc * 32 + fr, fq * 8);
;     ...
;     const char* uA = a_unit(cur); int tbA = cur.k0 / BK;
;     const char* cA = a_tile(uA, tbA); const char* cB = (const char*)g.Bt + (size_t)cur.pn * tstepB + b_k0(cur.k0);
;     S.a_ready(cur);
;     if constexpr (SP2) {
;         PG8_STAGE(PG8_SB(0, 0), cB, voffB); PG8_STAGE(PG8_SB(0, 1), cB + hstepB, voffB); PG8_STAGE(PG8_SA(0, 0), cA, voffA); PG8_STAGE(PG8_SA(0, 1), cA + hstepA, voffA);
;         if (wr == 1) PG8_BAR;
;         PG8_WAIT_V(2); PG8_BAR;
;         PG8_STAGE(PG8_SB(1, 0), cB + kstepB, voffB); PG8_STAGE(PG8_SA(1, 0), a_tile(uA, tbA + 1), voffA); PG8_STAGE(PG8_SB(1, 1), cB + hstepB + kstepB, voffB);
;         PG8_WAIT_V(6); PG8_BAR;
.LBB0_1158:
	s_and_b32 s47, s8, 3
	s_lshl_b32 s10, s7, 13
	s_lshl_b32 s11, s47, 12
	s_add_u32 s8, s28, 0x8000
	s_addc_u32 s9, s29, 0
	s_add_i32 m0, s25, 0x18000
	v_lshl_add_u64 v[14:15], s[8:9], 0, v[134:135]
	global_load_lds_dwordx4 v[14:15], off
	v_lshl_add_u64 v[14:15], s[8:9], 0, v[130:131]
	s_add_i32 m0, s25, 0x1a000
	s_mov_b64 s[8:9], 0x80
	s_add_i32 s48, s25, 0x8000
	global_load_lds_dwordx4 v[14:15], off
	v_lshl_add_u64 v[2:3], v[2:3], 0, s[8:9]
	s_mov_b32 m0, s48
	s_add_i32 s49, s25, 0xa000
	global_load_lds_dwordx4 v[2:3], off
	v_lshl_add_u64 v[2:3], v[4:5], 0, s[8:9]
	s_add_u32 s8, s28, 0xc000
	s_mov_b32 m0, s49
	s_addc_u32 s9, s29, 0
	global_load_lds_dwordx4 v[2:3], off
	s_add_i32 m0, s25, 0x1c000
	s_nop 0
	global_load_lds_dwordx4 v134, s[8:9]
	s_add_i32 m0, s25, 0x1e000
	v_lshrrev_b32_e32 v4, 1, v9
	global_load_lds_dwordx4 v130, s[8:9]
	s_waitcnt vmcnt(8)
	s_barrier
	v_and_b32_e32 v4, 24, v4
	v_and_b32_e32 v3, 15, v9
	v_lshlrev_b32_e32 v5, 1, v4
	v_lshl_or_b32 v2, s7, 6, v3
	v_lshl_or_b32 v5, v3, 6, v5
	v_cmp_lt_u32_e64 s[8:9], 7, v3
	v_mov_b32_e32 v3, 0xfffffc40
	v_or_b32_e32 v14, 16, v2
	v_cndmask_b32_e64 v140, 0, v3, s[8:9]
	v_mov_b32_e32 v3, 0x400
	v_cndmask_b32_e64 v142, v3, 64, s[8:9]
	v_ashrrev_i32_e32 v3, 31, v2
	v_ashrrev_i32_e32 v15, 31, v14
	v_lshlrev_b64 v[144:145], 7, v[2:3]
	v_lshlrev_b64 v[146:147], 7, v[14:15]
	v_or_b32_e32 v14, 32, v2
	v_or_b32_e32 v2, 48, v2
	v_ashrrev_i32_e32 v3, 31, v2
	v_lshlrev_b64 v[150:151], 7, v[2:3]
	v_lshlrev_b32_e32 v2, 15, v10
	v_and_b32_e32 v2, 0xffff0000, v2
	v_lshl_add_u32 v2, v11, 12, v2
	v_and_b32_e32 v3, 1, v10
	v_lshl_or_b32 v2, v3, 6, v2
	v_lshl_add_u64 v[152:153], v[144:145], 0, s[4:5]
	s_mov_b64 s[4:5], 0x4800
	v_lshl_add_u32 v138, v12, 1, v2
	v_lshlrev_b32_e32 v2, 15, v6
	v_lshl_add_u64 v[154:155], v[144:145], 0, s[4:5]
	s_mov_b64 s[4:5], 0x5000
	v_and_b32_e32 v2, 0xffff0000, v2
	v_lshlrev_b32_e32 v9, 2, v9
	v_lshl_add_u64 v[156:157], v[144:145], 0, s[4:5]
	s_mov_b64 s[4:5], 0x5800
	v_lshl_add_u32 v2, v7, 12, v2
	v_and_b32_e32 v3, 1, v6
	v_and_b32_e32 v9, 32, v9
	s_waitcnt vmcnt(6)
	s_cmpk_lt_u32 s6, 0x100
	v_lshl_add_u64 v[158:159], v[144:145], 0, s[4:5]
	s_mov_b64 s[4:5], 0x80080
	v_lshl_or_b32 v2, v3, 6, v2
	v_bitop3_b32 v13, v5, s10, v9 bitop3:0xde
	v_bitop3_b32 v168, v5, s11, v9 bitop3:0xde
	s_cselect_b64 s[6:7], -1, 0
	v_ashrrev_i32_e32 v15, 31, v14
	v_lshl_add_u64 v[160:161], v[138:139], 0, s[4:5]
	v_lshl_add_u32 v138, v8, 1, v2
	s_add_i32 s55, s72, s42
	v_cndmask_b32_e64 v141, 0, -1, s[8:9]
	v_mov_b32_e32 v143, v139
	v_lshlrev_b64 v[148:149], 7, v[14:15]
	v_lshl_add_u64 v[162:163], v[138:139], 0, s[4:5]
	v_add_u32_e32 v169, s72, v168
	v_add_u32_e32 v170, s73, v168
	v_add_u32_e32 v171, 0, v13
	v_lshlrev_b32_e32 v138, 1, v4
	s_add_i32 s50, s25, 0xc000
	s_add_i32 s51, s25, 0xe000
	s_add_i32 s56, s55, 0x2000
	s_barrier
	s_branch .LBB0_1161

; __device__ __forceinline__ int tid_fresh() { int t = threadIdx.x; asm volatile("" : "+v"(t)); return t; }
; #define PG8_WAIT_V(n) asm volatile("s_waitcnt vmcnt(" #n ")" ::: "memory")
; #define PG8_BAR __builtin_amdgcn_s_barrier()
; template <class Epi, class Sched, bool ABLK = false, bool ALIGN_EPI = true, bool SP2 = true, bool BBLK = true>
; __device__ __forceinline__ void gemm_phase(LAS unsigned char* lds, const Gemm g, const Sched& S, const Epi& E) {
;     const int tid = tid_fresh(), wid = __builtin_amdgcn_readfirstlane(tid >> 6), lane = tid & 63, wr = wid >> 2, wc = wid & 3, fr = lane & 15, fq = lane >> 4;
;     unsigned voffA[2], voffB[2];
; #pragma unroll
;     for (int i = 0; i < 2; ++i) { int R, C; stage_rc(tid * 16 + i * 8192, R, C); const int r32 = Epi::PERM ? perm32(R & 31) : (R & 31);
;         const int Rb = Epi::ADJ ? 64 * (R >> 5) + r32 : (R & ~31) + r32;
;         voffA[i] = (unsigned)(R * (ABLK ? 64 : g.lda) + C) * 2u; voffB[i] = BBLK ? (unsigned)(R * 64 + C) * 2u : (unsigned)(Rb * g.ldb + C) * 2u; }
;     const size_t kstep = (size_t)(BK * 2);
;     const size_t hstepA = (size_t)HALF * (ABLK ? 64 : g.lda) * 2, hstepB = BBLK ? (size_t)16384 : (size_t)(Epi::ADJ ? 32 : HALF) * g.ldb * 2;
;     const size_t tstepB = BBLK ? ((size_t)g.ldb / 64) * 32768 : (size_t)BM * g.ldb * 2;
;     const size_t kstepB = BBLK ? (size_t)32768 : kstep;
;     auto b_k0 = [&](int k0) -> size_t { return BBLK ? (size_t)(k0 / BK) * 32768 : (size_t)k0 * 2; };
;     const unsigned ldsw = (unsigned)wid * 1024u;
;     const int aoff = lds_byte(wr * 64 + fr, fq * 8), boff = lds_byte(wc * 32 + fr, fq * 8);
;     ...
;     const char* uA = a_unit(cur); int tbA = cur.k0 / BK;
;     const char* cA = a_tile(uA, tbA); const char* cB = (const char*)g.Bt + (size_t)cur.pn * tstepB + b_k0(cur.k0);
;     S.a_ready(cur);
;     if constexpr (SP2) {
;         PG8_STAGE(PG8_SB(0, 0), cB, voffB); PG8_STAGE(PG8_SB(0, 1), cB + hstepB, voffB); PG8_STAGE(PG8_SA(0, 0), cA, voffA); PG8_STAGE(PG8_SA(0, 1), cA + hstepA, voffA);
;         if (wr == 1) PG8_BAR;
;         PG8_WAIT_V(2); PG8_BAR;
;         PG8_STAGE(PG8_SB(1, 0), cB + kstepB, voffB); PG8_STAGE(PG8_SA(1, 0), a_tile(uA, tbA + 1), voffA); PG8_STAGE(PG8_SB(1, 1), cB + hstepB + kstepB, voffB);
;         PG8_WAIT_V(6); PG8_BAR;
.LBB0_1225:
	s_and_b32 s5, s5, 3
	s_lshl_b32 s7, s6, 13
	s_lshl_b32 s10, s5, 12
	s_add_u32 s8, s22, 0x8000
	s_addc_u32 s9, s23, 0
	s_add_i32 m0, s35, 0x18000
	v_lshl_add_u64 v[10:11], s[8:9], 0, v[130:131]
	global_load_lds_dwordx4 v[10:11], off
	s_add_i32 m0, s35, 0x1a000
	v_lshl_add_u64 v[10:11], s[8:9], 0, v[132:133]
	s_add_u32 s8, s24, 0x8000
	s_addc_u32 s9, s25, 0
	s_add_i32 s41, s35, 0x8000
	global_load_lds_dwordx4 v[10:11], off
	s_mov_b32 m0, s41
	s_add_i32 s42, s35, 0xa000
	global_load_lds_dwordx4 v130, s[8:9]
	v_lshl_add_u64 v[10:11], s[8:9], 0, v[132:133]
	s_add_u32 s8, s22, 0xc000
	s_mov_b32 m0, s42
	s_addc_u32 s9, s23, 0
	global_load_lds_dwordx4 v[10:11], off
	s_add_i32 m0, s35, 0x1c000
	s_nop 0
	global_load_lds_dwordx4 v130, s[8:9]
	s_add_i32 m0, s35, 0x1e000
	v_and_b32_e32 v9, 15, v4
	global_load_lds_dwordx4 v132, s[8:9]
	s_waitcnt vmcnt(8)
	s_barrier
	v_lshrrev_b32_e32 v10, 1, v4
	v_and_b32_e32 v10, 24, v10
	v_lshlrev_b32_e32 v11, 1, v10
	v_lshl_or_b32 v146, s6, 6, v9
	v_lshl_or_b32 v11, v9, 6, v11
	v_cmp_lt_u32_e64 s[8:9], 7, v9
	v_mov_b32_e32 v9, 0xffff8040
	v_lshlrev_b32_e32 v4, 2, v4
	v_cndmask_b32_e64 v134, 0, v9, s[8:9]
	v_mov_b32_e32 v9, 0x8000
	v_cndmask_b32_e64 v136, v9, 64, s[8:9]
	v_lshlrev_b32_e32 v9, 10, v2
	v_and_b32_e32 v9, 0xfffff800, v9
	v_lshl_add_u32 v3, v3, 7, v9
	v_and_b32_e32 v2, 1, v2
	v_and_b32_e32 v4, 32, v4
	v_lshl_or_b32 v2, v2, 6, v3
	v_bitop3_b32 v147, v11, s10, v4 bitop3:0xde
	s_mov_b64 s[10:11], 0xc000
	v_lshl_add_u32 v2, v5, 1, v2
	v_mov_b32_e32 v3, v131
	v_lshl_add_u64 v[138:139], v[2:3], 0, s[10:11]
	v_lshlrev_b32_e32 v2, 10, v6
	v_and_b32_e32 v2, 0xfffff800, v2
	v_lshl_add_u32 v2, v7, 7, v2
	v_and_b32_e32 v3, 1, v6
	s_waitcnt vmcnt(6)
	v_lshl_or_b32 v2, v3, 6, v2
	v_bitop3_b32 v4, v11, s7, v4 bitop3:0xde
	s_cmpk_lt_u32 s4, 0x100
	v_lshl_add_u32 v2, v8, 1, v2
	v_mov_b32_e32 v3, v131
	s_cselect_b64 s[6:7], -1, 0
	v_cndmask_b32_e64 v135, 0, -1, s[8:9]
	v_mov_b32_e32 v137, v131
	v_lshl_or_b32 v148, s5, 6, v10
	v_lshl_add_u64 v[140:141], v[2:3], 0, s[10:11]
	s_mov_b64 s[4:5], -1
	s_movk_i32 s44, 0x80
	v_add_u32_e32 v149, s72, v147
	v_add_u32_e32 v150, s73, v147
	v_add_u32_e32 v151, 0, v4
	s_mov_b64 s[14:15], 0xb0000
	s_mov_b32 s45, s82
	s_mov_b32 s26, 0
	s_barrier
	s_branch .LBB0_1228

; __device__ __forceinline__ int tid_fresh() { int t = threadIdx.x; asm volatile("" : "+v"(t)); return t; }
; #define PG8_WAIT_V(n) asm volatile("s_waitcnt vmcnt(" #n ")" ::: "memory")
; #define PG8_BAR __builtin_amdgcn_s_barrier()
; template <class Epi, class Sched, bool ABLK = false, bool ALIGN_EPI = true, bool SP2 = true, bool BBLK = true>
; __device__ __forceinline__ void gemm_phase(LAS unsigned char* lds, const Gemm g, const Sched& S, const Epi& E) {
;     const int tid = tid_fresh(), wid = __builtin_amdgcn_readfirstlane(tid >> 6), lane = tid & 63, wr = wid >> 2, wc = wid & 3, fr = lane & 15, fq = lane >> 4;
;     unsigned voffA[2], voffB[2];
; #pragma unroll
;     for (int i = 0; i < 2; ++i) { int R, C; stage_rc(tid * 16 + i * 8192, R, C); const int r32 = Epi::PERM ? perm32(R & 31) : (R & 31);
;         const int Rb = Epi::ADJ ? 64 * (R >> 5) + r32 : (R & ~31) + r32;
;         voffA[i] = (unsigned)(R * (ABLK ? 64 : g.lda) + C) * 2u; voffB[i] = BBLK ? (unsigned)(R * 64 + C) * 2u : (unsigned)(Rb * g.ldb + C) * 2u; }
;     const size_t kstep = (size_t)(BK * 2);
;     const size_t hstepA = (size_t)HALF * (ABLK ? 64 : g.lda) * 2, hstepB = BBLK ? (size_t)16384 : (size_t)(Epi::ADJ ? 32 : HALF) * g.ldb * 2;
;     const size_t tstepB = BBLK ? ((size_t)g.ldb / 64) * 32768 : (size_t)BM * g.ldb * 2;
;     const size_t kstepB = BBLK ? (size_t)32768 : kstep;
;     auto b_k0 = [&](int k0) -> size_t { return BBLK ? (size_t)(k0 / BK) * 32768 : (size_t)k0 * 2; };
;     const unsigned ldsw = (unsigned)wid * 1024u;
;     const int aoff = lds_byte(wr * 64 + fr, fq * 8), boff = lds_byte(wc * 32 + fr, fq * 8);
;     ...
;     const char* uA = a_unit(cur); int tbA = cur.k0 / BK;
;     const char* cA = a_tile(uA, tbA); const char* cB = (const char*)g.Bt + (size_t)cur.pn * tstepB + b_k0(cur.k0);
;     S.a_ready(cur);
;     if constexpr (SP2) {
;         PG8_STAGE(PG8_SB(0, 0), cB, voffB); PG8_STAGE(PG8_SB(0, 1), cB + hstepB, voffB); PG8_STAGE(PG8_SA(0, 0), cA, voffA); PG8_STAGE(PG8_SA(0, 1), cA + hstepA, voffA);
;         if (wr == 1) PG8_BAR;
;         PG8_WAIT_V(2); PG8_BAR;
;         PG8_STAGE(PG8_SB(1, 0), cB + kstepB, voffB); PG8_STAGE(PG8_SA(1, 0), a_tile(uA, tbA + 1), voffA); PG8_STAGE(PG8_SB(1, 1), cB + hstepB + kstepB, voffB);
;         PG8_WAIT_V(6); PG8_BAR;
.LBB0_1349:
	s_add_u32 s10, s68, 0x2fb20000
	s_addc_u32 s11, s69, 0
	s_and_b32 s14, s8, 3
	s_lshl_b32 s12, s5, 13
	s_lshl_b32 s13, s14, 12
	s_add_u32 s8, s40, 0x8000
	s_addc_u32 s9, s41, 0
	s_add_i32 m0, s31, 0x18000
	v_lshl_add_u64 v[14:15], s[8:9], 0, v[134:135]
	global_load_lds_dwordx4 v[14:15], off
	v_lshl_add_u64 v[14:15], s[8:9], 0, v[130:131]
	s_add_i32 m0, s31, 0x1a000
	s_mov_b64 s[8:9], 0x80
	s_add_i32 s54, s31, 0x8000
	s_add_i32 s55, s31, 0xa000
	global_load_lds_dwordx4 v[14:15], off
	v_lshl_add_u64 v[4:5], v[4:5], 0, s[8:9]
	s_mov_b32 m0, s54
	v_lshl_add_u64 v[2:3], v[2:3], 0, s[8:9]
	s_add_u32 s8, s40, 0xc000
	global_load_lds_dwordx4 v[4:5], off
	s_mov_b32 m0, s55
	s_addc_u32 s9, s41, 0
	global_load_lds_dwordx4 v[2:3], off
	s_add_i32 m0, s31, 0x1c000
	s_nop 0
	global_load_lds_dwordx4 v134, s[8:9]
	s_add_i32 m0, s31, 0x1e000
	v_lshlrev_b32_e32 v5, 2, v9
	global_load_lds_dwordx4 v130, s[8:9]
	s_waitcnt vmcnt(8)
	s_barrier
	v_lshrrev_b32_e32 v3, 1, v9
	v_and_b32_e32 v3, 24, v3
	v_and_b32_e32 v2, 15, v9
	v_lshlrev_b32_e32 v4, 1, v3
	v_lshl_or_b32 v160, s5, 6, v2
	v_lshl_or_b32 v4, v2, 6, v4
	v_cmp_lt_u32_e64 s[8:9], 7, v2
	v_mov_b32_e32 v2, 0xffff8040
	v_lshl_or_b32 v162, s14, 6, v3
	v_cndmask_b32_e64 v140, 0, v2, s[8:9]
	v_mov_b32_e32 v2, 0x8000
	v_cndmask_b32_e64 v142, v2, 64, s[8:9]
	v_lshlrev_b32_e32 v2, 15, v10
	v_and_b32_e32 v2, 0xffff0000, v2
	v_lshl_add_u32 v2, v11, 12, v2
	v_and_b32_e32 v3, 1, v10
	v_lshl_or_b32 v2, v3, 6, v2
	v_lshl_add_u32 v138, v12, 1, v2
	v_lshlrev_b32_e32 v2, 15, v6
	v_and_b32_e32 v2, 0xffff0000, v2
	v_lshl_add_u32 v2, v7, 12, v2
	v_and_b32_e32 v3, 1, v6
	v_and_b32_e32 v5, 32, v5
	s_waitcnt vmcnt(6)
	s_cmpk_lt_u32 s4, 0x100
	s_mov_b64 s[4:5], 0x80080
	v_lshl_or_b32 v2, v3, 6, v2
	v_bitop3_b32 v9, v4, s12, v5 bitop3:0xde
	v_bitop3_b32 v161, v4, s13, v5 bitop3:0xde
	v_lshl_add_u64 v[144:145], v[138:139], 0, s[4:5]
	v_lshl_add_u32 v138, v8, 1, v2
	s_cselect_b64 s[12:13], -1, 0
	v_cndmask_b32_e64 v141, 0, -1, s[8:9]
	v_mov_b32_e32 v143, v139
	v_lshl_add_u64 v[146:147], v[138:139], 0, s[4:5]
	v_add_u32_e32 v163, s72, v161
	v_add_u32_e32 v164, s73, v161
	v_add_u32_e32 v165, 0, v9
	s_mov_b64 s[14:15], 0x90000
	s_mov_b64 s[16:17], 0xa0000
	s_mov_b64 s[18:19], 0xb0000
	s_barrier
	s_branch .LBB0_1352

; #define PG8_STAGE(bufoff, gbase, voff) do { _Pragma("unroll") for (int _i = 0; _i < 2; ++_i) \
;         __builtin_amdgcn_global_load_lds((const unsigned*)((const char*)(gbase) + (voff)[_i]), (LAS unsigned*)(lds + (bufoff) + ldsw + _i * 8192), 16, 0, 0); } while (0)
; #define PG8_WAIT_V(n) asm volatile("s_waitcnt vmcnt(" #n ")" ::: "memory")
; #define PG8_BAR __builtin_amdgcn_s_barrier()
; template <class Epi, class Sched, bool ABLK = false, bool ALIGN_EPI = true, bool SP2 = true, bool BBLK = true>
; __device__ __forceinline__ void gemm_phase(LAS unsigned char* lds, const Gemm g, const Sched& S, const Epi& E) {
;     ...
;     const unsigned ldsw = (unsigned)wid * 1024u;
;     const int aoff = lds_byte(wr * 64 + fr, fq * 8), boff = lds_byte(wc * 32 + fr, fq * 8);
;     ...
;         PG8_STAGE(PG8_SB(0, 0), cB, voffB); PG8_STAGE(PG8_SB(0, 1), cB + hstepB, voffB); PG8_STAGE(PG8_SA(0, 0), cA, voffA); PG8_STAGE(PG8_SA(0, 1), cA + hstepA, voffA);
;         if (wr == 1) PG8_BAR;
;         PG8_WAIT_V(2); PG8_BAR;
;         PG8_STAGE(PG8_SB(1, 0), cB + kstepB, voffB); PG8_STAGE(PG8_SA(1, 0), a_tile(uA, tbA + 1), voffA); PG8_STAGE(PG8_SB(1, 1), cB + hstepB + kstepB, voffB);
;         PG8_WAIT_V(6); PG8_BAR;
.LBB0_1712:
	s_and_b32 s5, s5, 3
	s_lshl_b32 s7, s6, 13
	s_lshl_b32 s10, s5, 12
	s_add_u32 s12, s68, 0x3c900000
	s_addc_u32 s13, s69, 0
	s_add_u32 s8, s26, 0x8000
	s_addc_u32 s9, s27, 0
	s_add_i32 m0, s40, 0x18000
	v_lshl_add_u64 v[14:15], s[8:9], 0, v[132:133]
	global_load_lds_dwordx4 v[14:15], off
	v_lshl_add_u64 v[14:15], s[8:9], 0, v[136:137]
	s_add_i32 m0, s40, 0x1a000
	s_mov_b64 s[8:9], 0x80
	s_add_i32 s44, s40, 0x8000
	global_load_lds_dwordx4 v[14:15], off
	v_lshl_add_u64 v[2:3], v[2:3], 0, s[8:9]
	s_mov_b32 m0, s44
	s_add_i32 s45, s40, 0xa000
	global_load_lds_dwordx4 v[2:3], off
	v_lshl_add_u64 v[2:3], v[4:5], 0, s[8:9]
	s_add_u32 s8, s26, 0xc000
	s_mov_b32 m0, s45
	s_addc_u32 s9, s27, 0
	global_load_lds_dwordx4 v[2:3], off
	s_add_i32 m0, s40, 0x1c000
	s_nop 0
	global_load_lds_dwordx4 v132, s[8:9]
	s_add_i32 m0, s40, 0x1e000
	s_cmpk_lt_u32 s4, 0x100
	global_load_lds_dwordx4 v136, s[8:9]
	s_waitcnt vmcnt(8)
	s_barrier
	v_lshrrev_b32_e32 v3, 1, v7
	v_and_b32_e32 v3, 24, v3
	v_and_b32_e32 v2, 15, v7
	v_lshlrev_b32_e32 v4, 1, v3
	v_lshl_or_b32 v1, s6, 6, v2
	v_lshl_or_b32 v4, v2, 6, v4
	v_cmp_lt_u32_e64 s[8:9], 7, v2
	v_mov_b32_e32 v2, 0xffff8040
	v_lshl_or_b32 v151, s5, 6, v3
	v_cndmask_b32_e64 v138, 0, v2, s[8:9]
	v_mov_b32_e32 v2, 0x8000
	v_cndmask_b32_e64 v140, v2, 64, s[8:9]
	v_lshlrev_b32_e32 v2, 15, v6
	v_and_b32_e32 v2, 0xffff0000, v2
	v_lshl_add_u32 v2, v8, 12, v2
	v_and_b32_e32 v3, 1, v6
	v_lshl_or_b32 v2, v3, 6, v2
	v_lshl_add_u32 v2, v9, 1, v2
	v_mov_b32_e32 v3, v133
	s_mov_b64 s[4:5], 0x80080
	v_lshl_add_u64 v[142:143], v[2:3], 0, s[4:5]
	v_lshlrev_b32_e32 v2, 15, v10
	v_and_b32_e32 v2, 0xffff0000, v2
	v_lshlrev_b32_e32 v5, 2, v7
	v_lshl_add_u32 v2, v11, 12, v2
	v_and_b32_e32 v3, 1, v10
	v_and_b32_e32 v5, 32, v5
	s_waitcnt vmcnt(6)
	v_lshl_or_b32 v2, v3, 6, v2
	v_bitop3_b32 v150, v4, s10, v5 bitop3:0xde
	v_bitop3_b32 v4, v4, s7, v5 bitop3:0xde
	v_lshl_add_u32 v2, v12, 1, v2
	v_mov_b32_e32 v3, v133
	s_cselect_b64 s[6:7], -1, 0
	v_cndmask_b32_e64 v139, 0, -1, s[8:9]
	v_mov_b32_e32 v141, v133
	v_lshl_add_u64 v[144:145], v[2:3], 0, s[4:5]
	s_mov_b64 s[4:5], -1
	v_add_u32_e32 v152, s72, v150
	v_add_u32_e32 v153, s73, v150
	v_add_u32_e32 v154, 0, v4
	s_mov_b64 s[14:15], 0x90000
	s_mov_b64 s[16:17], 0xa0000
	s_mov_b64 s[18:19], 0xb0000
	s_mov_b32 s48, s82
	s_mov_b32 s30, 0
	s_barrier
	s_branch .LBB0_1715

; #define PG8_STAGE(bufoff, gbase, voff) do { _Pragma("unroll") for (int _i = 0; _i < 2; ++_i) \
;         __builtin_amdgcn_global_load_lds((const unsigned*)((const char*)(gbase) + (voff)[_i]), (LAS unsigned*)(lds + (bufoff) + ldsw + _i * 8192), 16, 0, 0); } while (0)
; #define PG8_WAIT_V(n) asm volatile("s_waitcnt vmcnt(" #n ")" ::: "memory")
; #define PG8_BAR __builtin_amdgcn_s_barrier()
; template <class Epi, class Sched, bool ABLK = false, bool ALIGN_EPI = true, bool SP2 = true, bool BBLK = true>
; __device__ __forceinline__ void gemm_phase(LAS unsigned char* lds, const Gemm g, const Sched& S, const Epi& E) {
;     ...
;     const unsigned ldsw = (unsigned)wid * 1024u;
;     const int aoff = lds_byte(wr * 64 + fr, fq * 8), boff = lds_byte(wc * 32 + fr, fq * 8);
;     ...
;         PG8_STAGE(PG8_SB(0, 0), cB, voffB); PG8_STAGE(PG8_SB(0, 1), cB + hstepB, voffB); PG8_STAGE(PG8_SA(0, 0), cA, voffA); PG8_STAGE(PG8_SA(0, 1), cA + hstepA, voffA);
;         if (wr == 1) PG8_BAR;
;         PG8_WAIT_V(2); PG8_BAR;
;         PG8_STAGE(PG8_SB(1, 0), cB + kstepB, voffB); PG8_STAGE(PG8_SA(1, 0), a_tile(uA, tbA + 1), voffA); PG8_STAGE(PG8_SB(1, 1), cB + hstepB + kstepB, voffB);
;         PG8_WAIT_V(6); PG8_BAR;
.LBB0_1836:
	s_and_b32 s44, s8, 3
	s_lshl_b32 s10, s7, 13
	s_lshl_b32 s11, s44, 12
	s_add_u32 s8, s28, 0x8000
	s_addc_u32 s9, s29, 0
	s_add_i32 m0, s25, 0x18000
	v_lshl_add_u64 v[12:13], s[8:9], 0, v[134:135]
	global_load_lds_dwordx4 v[12:13], off
	v_lshl_add_u64 v[12:13], s[8:9], 0, v[130:131]
	s_add_i32 m0, s25, 0x1a000
	s_mov_b64 s[8:9], 0x80
	s_add_i32 s45, s25, 0x8000
	global_load_lds_dwordx4 v[12:13], off
	v_lshl_add_u64 v[2:3], v[2:3], 0, s[8:9]
	s_mov_b32 m0, s45
	s_add_i32 s46, s25, 0xa000
	global_load_lds_dwordx4 v[2:3], off
	v_lshl_add_u64 v[2:3], v[4:5], 0, s[8:9]
	s_add_u32 s8, s28, 0xc000
	s_mov_b32 m0, s46
	s_addc_u32 s9, s29, 0
	global_load_lds_dwordx4 v[2:3], off
	s_add_i32 m0, s25, 0x1c000
	s_nop 0
	global_load_lds_dwordx4 v134, s[8:9]
	s_add_i32 m0, s25, 0x1e000
	v_lshrrev_b32_e32 v4, 1, v1
	global_load_lds_dwordx4 v130, s[8:9]
	s_waitcnt vmcnt(8)
	s_barrier
	v_and_b32_e32 v4, 24, v4
	v_and_b32_e32 v3, 15, v1
	v_lshlrev_b32_e32 v5, 1, v4
	v_lshl_or_b32 v2, s7, 6, v3
	v_lshl_or_b32 v5, v3, 6, v5
	v_cmp_lt_u32_e64 s[8:9], 7, v3
	v_mov_b32_e32 v3, 0xfffffc40
	v_or_b32_e32 v12, 16, v2
	v_cndmask_b32_e64 v140, 0, v3, s[8:9]
	v_mov_b32_e32 v3, 0x400
	v_cndmask_b32_e64 v142, v3, 64, s[8:9]
	v_ashrrev_i32_e32 v3, 31, v2
	v_ashrrev_i32_e32 v13, 31, v12
	v_lshlrev_b64 v[144:145], 7, v[2:3]
	v_lshlrev_b64 v[146:147], 7, v[12:13]
	v_or_b32_e32 v12, 32, v2
	v_or_b32_e32 v2, 48, v2
	v_ashrrev_i32_e32 v3, 31, v2
	v_lshlrev_b64 v[150:151], 7, v[2:3]
	v_lshlrev_b32_e32 v2, 15, v9
	v_and_b32_e32 v2, 0xffff0000, v2
	v_lshl_add_u32 v2, v10, 12, v2
	v_and_b32_e32 v3, 1, v9
	v_lshl_or_b32 v2, v3, 6, v2
	v_lshl_add_u64 v[152:153], v[144:145], 0, s[4:5]
	s_mov_b64 s[4:5], 0x4800
	v_lshl_add_u32 v138, v11, 1, v2
	v_lshlrev_b32_e32 v2, 15, v6
	v_lshl_add_u64 v[154:155], v[144:145], 0, s[4:5]
	s_mov_b64 s[4:5], 0x5000
	v_and_b32_e32 v2, 0xffff0000, v2
	v_lshlrev_b32_e32 v1, 2, v1
	v_lshl_add_u64 v[156:157], v[144:145], 0, s[4:5]
	s_mov_b64 s[4:5], 0x5800
	v_lshl_add_u32 v2, v7, 12, v2
	v_and_b32_e32 v3, 1, v6
	v_and_b32_e32 v1, 32, v1
	s_waitcnt vmcnt(6)
	s_cmpk_lt_u32 s6, 0x100
	v_lshl_add_u64 v[158:159], v[144:145], 0, s[4:5]
	s_mov_b64 s[4:5], 0x80080
	v_lshl_or_b32 v2, v3, 6, v2
	v_bitop3_b32 v14, v5, s10, v1 bitop3:0xde
	v_bitop3_b32 v1, v5, s11, v1 bitop3:0xde
	s_cselect_b64 s[6:7], -1, 0
	v_ashrrev_i32_e32 v13, 31, v12
	v_lshl_add_u64 v[160:161], v[138:139], 0, s[4:5]
	v_lshl_add_u32 v138, v8, 1, v2
	s_add_i32 s49, s72, s39
	v_cndmask_b32_e64 v141, 0, -1, s[8:9]
	v_mov_b32_e32 v143, v139
	v_lshlrev_b64 v[148:149], 7, v[12:13]
	v_lshl_add_u64 v[162:163], v[138:139], 0, s[4:5]
	v_add_u32_e32 v168, s72, v1
	v_add_u32_e32 v169, s73, v1
	v_add_u32_e32 v170, 0, v14
	v_lshlrev_b32_e32 v138, 1, v4
	s_add_i32 s47, s25, 0xc000
	s_add_i32 s48, s25, 0xe000
	s_add_i32 s50, s49, 0x2000
	s_barrier
	s_branch .LBB0_1839

; #define PG8_STAGE(bufoff, gbase, voff) do { _Pragma("unroll") for (int _i = 0; _i < 2; ++_i) \
;         __builtin_amdgcn_global_load_lds((const unsigned*)((const char*)(gbase) + (voff)[_i]), (LAS unsigned*)(lds + (bufoff) + ldsw + _i * 8192), 16, 0, 0); } while (0)
; #define PG8_WAIT_V(n) asm volatile("s_waitcnt vmcnt(" #n ")" ::: "memory")
; #define PG8_BAR __builtin_amdgcn_s_barrier()
; template <class Epi, class Sched, bool ABLK = false, bool ALIGN_EPI = true, bool SP2 = true, bool BBLK = true>
; __device__ __forceinline__ void gemm_phase(LAS unsigned char* lds, const Gemm g, const Sched& S, const Epi& E) {
;     ...
;     const unsigned ldsw = (unsigned)wid * 1024u;
;     const int aoff = lds_byte(wr * 64 + fr, fq * 8), boff = lds_byte(wc * 32 + fr, fq * 8);
;     ...
;         PG8_STAGE(PG8_SB(0, 0), cB, voffB); PG8_STAGE(PG8_SB(0, 1), cB + hstepB, voffB); PG8_STAGE(PG8_SA(0, 0), cA, voffA); PG8_STAGE(PG8_SA(0, 1), cA + hstepA, voffA);
;         if (wr == 1) PG8_BAR;
;         PG8_WAIT_V(2); PG8_BAR;
;         PG8_STAGE(PG8_SB(1, 0), cB + kstepB, voffB); PG8_STAGE(PG8_SA(1, 0), a_tile(uA, tbA + 1), voffA); PG8_STAGE(PG8_SB(1, 1), cB + hstepB + kstepB, voffB);
;         PG8_WAIT_V(6); PG8_BAR;
.LBB0_1903:
	s_and_b32 s5, s5, 3
	s_lshl_b32 s7, s6, 13
	s_lshl_b32 s10, s5, 12
	s_add_u32 s8, s30, 0x8000
	s_addc_u32 s9, s31, 0
	s_add_i32 m0, s41, 0x18000
	v_lshl_add_u64 v[10:11], s[8:9], 0, v[130:131]
	global_load_lds_dwordx4 v[10:11], off
	s_add_i32 m0, s41, 0x1a000
	v_lshl_add_u64 v[10:11], s[8:9], 0, v[132:133]
	s_add_u32 s8, s34, 0x8000
	s_addc_u32 s9, s35, 0
	s_add_i32 s45, s41, 0x8000
	global_load_lds_dwordx4 v[10:11], off
	s_mov_b32 m0, s45
	s_add_i32 s46, s41, 0xa000
	global_load_lds_dwordx4 v130, s[8:9]
	v_lshl_add_u64 v[10:11], s[8:9], 0, v[132:133]
	s_add_u32 s8, s30, 0xc000
	s_mov_b32 m0, s46
	s_addc_u32 s9, s31, 0
	global_load_lds_dwordx4 v[10:11], off
	s_add_i32 m0, s41, 0x1c000
	s_nop 0
	global_load_lds_dwordx4 v130, s[8:9]
	s_add_i32 m0, s41, 0x1e000
	v_and_b32_e32 v9, 15, v4
	global_load_lds_dwordx4 v132, s[8:9]
	s_waitcnt vmcnt(8)
	s_barrier
	v_lshrrev_b32_e32 v10, 1, v4
	v_and_b32_e32 v10, 24, v10
	v_lshlrev_b32_e32 v11, 1, v10
	v_lshl_or_b32 v1, s6, 6, v9
	v_lshl_or_b32 v11, v9, 6, v11
	v_cmp_lt_u32_e64 s[8:9], 7, v9
	v_mov_b32_e32 v9, 0xffff8040
	v_lshlrev_b32_e32 v4, 2, v4
	v_cndmask_b32_e64 v134, 0, v9, s[8:9]
	v_mov_b32_e32 v9, 0x8000
	v_cndmask_b32_e64 v136, v9, 64, s[8:9]
	v_lshlrev_b32_e32 v9, 10, v2
	v_and_b32_e32 v9, 0xfffff800, v9
	v_lshl_add_u32 v3, v3, 7, v9
	v_and_b32_e32 v2, 1, v2
	v_and_b32_e32 v4, 32, v4
	v_lshl_or_b32 v2, v2, 6, v3
	v_bitop3_b32 v146, v11, s10, v4 bitop3:0xde
	s_mov_b64 s[10:11], 0xc000
	v_lshl_add_u32 v2, v5, 1, v2
	v_mov_b32_e32 v3, v131
	v_lshl_add_u64 v[138:139], v[2:3], 0, s[10:11]
	v_lshlrev_b32_e32 v2, 10, v6
	v_and_b32_e32 v2, 0xfffff800, v2
	v_lshl_add_u32 v2, v7, 7, v2
	v_and_b32_e32 v3, 1, v6
	s_waitcnt vmcnt(6)
	v_lshl_or_b32 v2, v3, 6, v2
	v_bitop3_b32 v4, v11, s7, v4 bitop3:0xde
	s_cmpk_lt_u32 s4, 0x100
	v_lshl_add_u32 v2, v8, 1, v2
	v_mov_b32_e32 v3, v131
	s_cselect_b64 s[6:7], -1, 0
	v_cndmask_b32_e64 v135, 0, -1, s[8:9]
	v_mov_b32_e32 v137, v131
	v_lshl_or_b32 v147, s5, 6, v10
	v_lshl_add_u64 v[140:141], v[2:3], 0, s[10:11]
	s_mov_b64 s[4:5], -1
	s_movk_i32 s48, 0x80
	v_add_u32_e32 v148, s72, v146
	v_add_u32_e32 v149, s73, v146
	v_add_u32_e32 v150, 0, v4
	s_mov_b64 s[14:15], 0x30000
	s_mov_b64 s[16:17], 0x80000
	s_mov_b64 s[18:19], 0x90000
	s_mov_b64 s[20:21], 0xa0000
	s_mov_b64 s[22:23], 0xb0000
	s_mov_b32 s49, s82
	s_mov_b32 s36, 0
	s_barrier
	s_branch .LBB0_1906

; #define PG8_STAGE(bufoff, gbase, voff) do { _Pragma("unroll") for (int _i = 0; _i < 2; ++_i) \
;         __builtin_amdgcn_global_load_lds((const unsigned*)((const char*)(gbase) + (voff)[_i]), (LAS unsigned*)(lds + (bufoff) + ldsw + _i * 8192), 16, 0, 0); } while (0)
; #define PG8_WAIT_V(n) asm volatile("s_waitcnt vmcnt(" #n ")" ::: "memory")
; #define PG8_BAR __builtin_amdgcn_s_barrier()
; template <class Epi, class Sched, bool ABLK = false, bool ALIGN_EPI = true, bool SP2 = true, bool BBLK = true>
; __device__ __forceinline__ void gemm_phase(LAS unsigned char* lds, const Gemm g, const Sched& S, const Epi& E) {
;     ...
;     const unsigned ldsw = (unsigned)wid * 1024u;
;     const int aoff = lds_byte(wr * 64 + fr, fq * 8), boff = lds_byte(wc * 32 + fr, fq * 8);
;     ...
;         PG8_STAGE(PG8_SB(0, 0), cB, voffB); PG8_STAGE(PG8_SB(0, 1), cB + hstepB, voffB); PG8_STAGE(PG8_SA(0, 0), cA, voffA); PG8_STAGE(PG8_SA(0, 1), cA + hstepA, voffA);
;         if (wr == 1) PG8_BAR;
;         PG8_WAIT_V(2); PG8_BAR;
;         PG8_STAGE(PG8_SB(1, 0), cB + kstepB, voffB); PG8_STAGE(PG8_SA(1, 0), a_tile(uA, tbA + 1), voffA); PG8_STAGE(PG8_SB(1, 1), cB + hstepB + kstepB, voffB);
;         PG8_WAIT_V(6); PG8_BAR;
.LBB0_2132:
	s_lshl_b32 s6, s6, 5
	s_and_b32 s11, s6, 0x60
	s_lshl_b32 s10, s5, 13
	s_lshl_b32 s12, s11, 7
	s_add_u32 s6, s26, 0x8000
	s_addc_u32 s7, s27, 0
	s_add_i32 m0, s21, 0x18000
	v_lshl_add_u64 v[14:15], s[6:7], 0, v[134:135]
	global_load_lds_dwordx4 v[14:15], off
	v_lshl_add_u64 v[14:15], s[6:7], 0, v[130:131]
	s_add_i32 m0, s21, 0x1a000
	s_mov_b64 s[6:7], 0x80
	s_add_i32 s42, s21, 0x8000
	global_load_lds_dwordx4 v[14:15], off
	v_lshl_add_u64 v[2:3], v[2:3], 0, s[6:7]
	s_mov_b32 m0, s42
	s_add_i32 s43, s21, 0xa000
	global_load_lds_dwordx4 v[2:3], off
	v_lshl_add_u64 v[2:3], v[4:5], 0, s[6:7]
	s_add_u32 s6, s26, 0xc000
	s_mov_b32 m0, s43
	s_addc_u32 s7, s27, 0
	global_load_lds_dwordx4 v[2:3], off
	s_add_i32 m0, s21, 0x1c000
	s_nop 0
	global_load_lds_dwordx4 v134, s[6:7]
	s_add_i32 m0, s21, 0x1e000
	s_cmpk_lt_u32 s4, 0x100
	global_load_lds_dwordx4 v130, s[6:7]
	s_waitcnt vmcnt(8)
	s_barrier
	v_lshrrev_b32_e32 v3, 1, v6
	v_and_b32_e32 v3, 24, v3
	v_and_b32_e32 v2, 15, v6
	v_lshlrev_b32_e32 v4, 1, v3
	v_lshl_or_b32 v1, s5, 6, v2
	v_lshl_or_b32 v2, v2, 6, v4
	v_lshlrev_b32_e32 v4, 2, v6
	v_and_b32_e32 v4, 32, v4
	v_bitop3_b32 v5, v2, s10, v4 bitop3:0xde
	v_bitop3_b32 v146, v2, s12, v4 bitop3:0xde
	v_lshlrev_b32_e32 v2, 15, v10
	v_and_b32_e32 v2, 0xffff0000, v2
	v_or_b32_e32 v147, s11, v3
	v_lshl_add_u32 v2, v11, 12, v2
	v_and_b32_e32 v3, 1, v10
	v_lshl_or_b32 v2, v3, 6, v2
	v_lshl_add_u32 v2, v12, 1, v2
	v_mov_b32_e32 v3, v135
	s_mov_b64 s[4:5], 0x80080
	v_lshl_add_u64 v[138:139], v[2:3], 0, s[4:5]
	v_lshlrev_b32_e32 v2, 15, v7
	v_and_b32_e32 v2, 0xffff0000, v2
	v_lshl_add_u32 v2, v8, 12, v2
	v_and_b32_e32 v3, 1, v7
	s_waitcnt vmcnt(6)
	v_lshl_or_b32 v2, v3, 6, v2
	v_lshl_add_u32 v2, v9, 1, v2
	v_mov_b32_e32 v3, v135
	s_cselect_b64 s[6:7], -1, 0
	v_lshl_add_u64 v[140:141], v[2:3], 0, s[4:5]
	v_add_u32_e32 v148, s72, v146
	v_add_u32_e32 v149, s73, v146
	v_add_u32_e32 v150, 0, v5
	s_mov_b32 s44, 0x80000
	s_mov_b32 s45, 0x90000
	s_mov_b32 s46, 0xa0000
	s_add_i32 s47, s21, 0xc000
	s_barrier
	s_waitcnt vmcnt(0)
	s_branch .LBB0_2135

; #define PG8_STAGE(bufoff, gbase, voff) do { _Pragma("unroll") for (int _i = 0; _i < 2; ++_i) \
;         __builtin_amdgcn_global_load_lds((const unsigned*)((const char*)(gbase) + (voff)[_i]), (LAS unsigned*)(lds + (bufoff) + ldsw + _i * 8192), 16, 0, 0); } while (0)
; #define PG8_WAIT_V(n) asm volatile("s_waitcnt vmcnt(" #n ")" ::: "memory")
; #define PG8_BAR __builtin_amdgcn_s_barrier()
; template <class Epi, class Sched, bool ABLK = false, bool ALIGN_EPI = true, bool SP2 = true, bool BBLK = true>
; __device__ __forceinline__ void gemm_phase(LAS unsigned char* lds, const Gemm g, const Sched& S, const Epi& E) {
;     ...
;     const unsigned ldsw = (unsigned)wid * 1024u;
;     const int aoff = lds_byte(wr * 64 + fr, fq * 8), boff = lds_byte(wc * 32 + fr, fq * 8);
;     ...
;         PG8_STAGE(PG8_SB(0, 0), cB, voffB); PG8_STAGE(PG8_SB(0, 1), cB + hstepB, voffB); PG8_STAGE(PG8_SA(0, 0), cA, voffA); PG8_STAGE(PG8_SA(0, 1), cA + hstepA, voffA);
;         if (wr == 1) PG8_BAR;
;         PG8_WAIT_V(2); PG8_BAR;
;         PG8_STAGE(PG8_SB(1, 0), cB + kstepB, voffB); PG8_STAGE(PG8_SA(1, 0), a_tile(uA, tbA + 1), voffA); PG8_STAGE(PG8_SB(1, 1), cB + hstepB + kstepB, voffB);
;         PG8_WAIT_V(6); PG8_BAR;
.LBB0_2257:
	s_and_b32 s47, s10, 3
	s_lshl_b32 s12, s3, 13
	s_lshl_b32 s13, s47, 12
	s_add_u32 s10, s28, 0x8000
	s_addc_u32 s11, s29, 0
	s_add_i32 m0, s25, 0x18000
	v_lshl_add_u64 v[12:13], s[10:11], 0, v[134:135]
	global_load_lds_dwordx4 v[12:13], off
	v_lshl_add_u64 v[12:13], s[10:11], 0, v[130:131]
	s_add_i32 m0, s25, 0x1a000
	s_mov_b64 s[10:11], 0x80
	s_add_i32 s48, s25, 0x8000
	global_load_lds_dwordx4 v[12:13], off
	v_lshl_add_u64 v[2:3], v[2:3], 0, s[10:11]
	s_mov_b32 m0, s48
	s_add_i32 s49, s25, 0xa000
	global_load_lds_dwordx4 v[2:3], off
	v_lshl_add_u64 v[2:3], v[4:5], 0, s[10:11]
	s_add_u32 s10, s28, 0xc000
	s_mov_b32 m0, s49
	s_addc_u32 s11, s29, 0
	global_load_lds_dwordx4 v[2:3], off
	s_add_i32 m0, s25, 0x1c000
	s_nop 0
	global_load_lds_dwordx4 v134, s[10:11]
	s_add_i32 m0, s25, 0x1e000
	v_lshrrev_b32_e32 v4, 1, v1
	global_load_lds_dwordx4 v130, s[10:11]
	s_waitcnt vmcnt(8)
	s_barrier
	v_and_b32_e32 v4, 24, v4
	v_and_b32_e32 v3, 15, v1
	v_lshlrev_b32_e32 v5, 1, v4
	v_lshl_or_b32 v2, s3, 6, v3
	v_lshl_or_b32 v5, v3, 6, v5
	s_cmpk_lt_u32 s2, 0x100
	v_cmp_lt_u32_e64 s[2:3], 7, v3
	v_mov_b32_e32 v3, 0xfffffc40
	v_or_b32_e32 v12, 16, v2
	v_cndmask_b32_e64 v140, 0, v3, s[2:3]
	v_mov_b32_e32 v3, 0x400
	v_cndmask_b32_e64 v142, v3, 64, s[2:3]
	v_ashrrev_i32_e32 v3, 31, v2
	v_ashrrev_i32_e32 v13, 31, v12
	v_lshlrev_b64 v[144:145], 7, v[2:3]
	v_lshlrev_b64 v[146:147], 7, v[12:13]
	v_or_b32_e32 v12, 32, v2
	v_or_b32_e32 v2, 48, v2
	v_ashrrev_i32_e32 v3, 31, v2
	v_lshlrev_b64 v[150:151], 7, v[2:3]
	v_lshlrev_b32_e32 v2, 15, v9
	v_and_b32_e32 v2, 0xffff0000, v2
	v_lshl_add_u32 v2, v10, 12, v2
	v_and_b32_e32 v3, 1, v9
	v_lshl_or_b32 v2, v3, 6, v2
	v_lshl_add_u64 v[152:153], v[144:145], 0, s[4:5]
	s_mov_b64 s[4:5], 0x4800
	v_lshl_add_u32 v138, v11, 1, v2
	v_lshlrev_b32_e32 v2, 15, v6
	v_lshl_add_u64 v[154:155], v[144:145], 0, s[4:5]
	s_mov_b64 s[4:5], 0x5000
	v_and_b32_e32 v2, 0xffff0000, v2
	v_lshlrev_b32_e32 v1, 2, v1
	v_lshl_add_u64 v[156:157], v[144:145], 0, s[4:5]
	s_mov_b64 s[4:5], 0x5800
	v_lshl_add_u32 v2, v7, 12, v2
	v_and_b32_e32 v3, 1, v6
	v_and_b32_e32 v1, 32, v1
	s_waitcnt vmcnt(6)
	v_lshl_add_u64 v[158:159], v[144:145], 0, s[4:5]
	s_mov_b64 s[4:5], 0x80080
	v_lshl_or_b32 v2, v3, 6, v2
	v_bitop3_b32 v14, v5, s12, v1 bitop3:0xde
	v_bitop3_b32 v1, v5, s13, v1 bitop3:0xde
	s_cselect_b64 s[10:11], -1, 0
	v_ashrrev_i32_e32 v13, 31, v12
	v_lshl_add_u64 v[160:161], v[138:139], 0, s[4:5]
	v_lshl_add_u32 v138, v8, 1, v2
	s_add_i32 s52, s72, s40
	v_cndmask_b32_e64 v141, 0, -1, s[2:3]
	v_mov_b32_e32 v143, v139
	v_lshlrev_b64 v[148:149], 7, v[12:13]
	v_lshl_add_u64 v[162:163], v[138:139], 0, s[4:5]
	v_add_u32_e32 v168, s72, v1
	v_add_u32_e32 v169, s73, v1
	v_add_u32_e32 v170, 0, v14
	v_lshlrev_b32_e32 v138, 1, v4
	s_add_i32 s50, s25, 0xc000
	s_add_i32 s51, s25, 0xe000
	s_add_i32 s53, s52, 0x2000
	s_barrier
	s_branch .LBB0_2260

; #define PG8_STAGE(bufoff, gbase, voff) do { _Pragma("unroll") for (int _i = 0; _i < 2; ++_i) \
;         __builtin_amdgcn_global_load_lds((const unsigned*)((const char*)(gbase) + (voff)[_i]), (LAS unsigned*)(lds + (bufoff) + ldsw + _i * 8192), 16, 0, 0); } while (0)
; #define PG8_WAIT_V(n) asm volatile("s_waitcnt vmcnt(" #n ")" ::: "memory")
; #define PG8_BAR __builtin_amdgcn_s_barrier()
; template <class Epi, class Sched, bool ABLK = false, bool ALIGN_EPI = true, bool SP2 = true, bool BBLK = true>
; __device__ __forceinline__ void gemm_phase(LAS unsigned char* lds, const Gemm g, const Sched& S, const Epi& E) {
;     ...
;     const unsigned ldsw = (unsigned)wid * 1024u;
;     const int aoff = lds_byte(wr * 64 + fr, fq * 8), boff = lds_byte(wc * 32 + fr, fq * 8);
;     ...
;         PG8_STAGE(PG8_SB(0, 0), cB, voffB); PG8_STAGE(PG8_SB(0, 1), cB + hstepB, voffB); PG8_STAGE(PG8_SA(0, 0), cA, voffA); PG8_STAGE(PG8_SA(0, 1), cA + hstepA, voffA);
;         if (wr == 1) PG8_BAR;
;         PG8_WAIT_V(2); PG8_BAR;
;         PG8_STAGE(PG8_SB(1, 0), cB + kstepB, voffB); PG8_STAGE(PG8_SA(1, 0), a_tile(uA, tbA + 1), voffA); PG8_STAGE(PG8_SB(1, 1), cB + hstepB + kstepB, voffB);
;         PG8_WAIT_V(6); PG8_BAR;
.LBB0_2324:
	s_and_b32 s6, s4, 3
	s_lshl_b32 s7, s3, 13
	s_lshl_b32 s14, s6, 12
	s_add_u32 s12, s68, 0x3c900000
	s_addc_u32 s13, s69, 0
	s_add_u32 s4, s38, 0x8000
	s_addc_u32 s5, s39, 0
	s_add_i32 m0, s49, 0x18000
	v_lshl_add_u64 v[10:11], s[4:5], 0, v[130:131]
	global_load_lds_dwordx4 v[10:11], off
	s_add_i32 m0, s49, 0x1a000
	v_lshl_add_u64 v[10:11], s[4:5], 0, v[132:133]
	s_add_u32 s4, s40, 0x8000
	s_addc_u32 s5, s41, 0
	s_add_i32 s53, s49, 0x8000
	global_load_lds_dwordx4 v[10:11], off
	s_mov_b32 m0, s53
	s_add_i32 s54, s49, 0xa000
	global_load_lds_dwordx4 v130, s[4:5]
	v_lshl_add_u64 v[10:11], s[4:5], 0, v[132:133]
	s_add_u32 s4, s38, 0xc000
	s_mov_b32 m0, s54
	s_addc_u32 s5, s39, 0
	global_load_lds_dwordx4 v[10:11], off
	s_add_i32 m0, s49, 0x1c000
	s_nop 0
	global_load_lds_dwordx4 v130, s[4:5]
	s_add_i32 m0, s49, 0x1e000
	v_and_b32_e32 v9, 15, v4
	global_load_lds_dwordx4 v132, s[4:5]
	s_waitcnt vmcnt(8)
	s_barrier
	v_lshrrev_b32_e32 v10, 1, v4
	v_and_b32_e32 v10, 24, v10
	v_lshlrev_b32_e32 v11, 1, v10
	v_lshl_or_b32 v1, s3, 6, v9
	v_lshl_or_b32 v11, v9, 6, v11
	s_cmpk_lt_u32 s2, 0x100
	v_cmp_lt_u32_e64 s[2:3], 7, v9
	v_mov_b32_e32 v9, 0xffff8040
	s_mov_b64 s[4:5], 0xc000
	v_cndmask_b32_e64 v134, 0, v9, s[2:3]
	v_mov_b32_e32 v9, 0x8000
	v_cndmask_b32_e64 v136, v9, 64, s[2:3]
	v_lshlrev_b32_e32 v9, 10, v2
	v_and_b32_e32 v9, 0xfffff800, v9
	v_lshl_add_u32 v3, v3, 7, v9
	v_and_b32_e32 v2, 1, v2
	v_lshl_or_b32 v2, v2, 6, v3
	v_lshl_add_u32 v2, v5, 1, v2
	v_mov_b32_e32 v3, v131
	v_lshl_add_u64 v[138:139], v[2:3], 0, s[4:5]
	v_lshlrev_b32_e32 v2, 10, v6
	v_and_b32_e32 v2, 0xfffff800, v2
	v_lshlrev_b32_e32 v4, 2, v4
	v_lshl_add_u32 v2, v7, 7, v2
	v_and_b32_e32 v3, 1, v6
	v_and_b32_e32 v4, 32, v4
	s_waitcnt vmcnt(6)
	v_lshl_or_b32 v2, v3, 6, v2
	v_bitop3_b32 v146, v11, s14, v4 bitop3:0xde
	v_bitop3_b32 v4, v11, s7, v4 bitop3:0xde
	v_lshl_add_u32 v2, v8, 1, v2
	v_mov_b32_e32 v3, v131
	s_cselect_b64 s[14:15], -1, 0
	v_cndmask_b32_e64 v135, 0, -1, s[2:3]
	v_mov_b32_e32 v137, v131
	v_lshl_or_b32 v147, s6, 6, v10
	v_lshl_add_u64 v[140:141], v[2:3], 0, s[4:5]
	s_mov_b64 s[4:5], -1
	s_movk_i32 s56, 0x80
	s_mov_b64 s[16:17], 0x10000
	v_add_u32_e32 v148, s72, v146
	v_add_u32_e32 v149, s73, v146
	v_add_u32_e32 v150, 0, v4
	s_mov_b64 s[18:19], 0x20000
	s_mov_b64 s[20:21], 0x30000
	s_mov_b64 s[22:23], 0x80000
	s_mov_b64 s[24:25], 0x90000
	s_mov_b64 s[26:27], 0xa0000
	s_mov_b64 s[28:29], 0xb0000
	s_mov_b32 s42, 0
	s_barrier
	s_branch .LBB0_2327
